# sample attention units remapped: each XCD takes all 8 heads of 4 batch rows (whole cache rows per XCD) instead of one head of all rows
# speedup vs baseline: 1.0034x; 1.0034x over previous
; #define LAS __attribute__((address_space(3)))
;     __device__ __forceinline__ bf16* U() const { return (bf16*)(ws + WS_U); }
;     __device__ __forceinline__ bf16* KVt() const { return (bf16*)(ws + WS_KVT); }
; #define PHASE_BEGIN() do { int t_ = C.tid; asm volatile("" : "+v"(t_)); C.tid = t_; C.lane = t_ & 63; C.wave = __builtin_amdgcn_readfirstlane(t_ >> 6); \
;         int g_ = C.G, b_ = C.bid; asm volatile("" : "+s"(g_), "+s"(b_)); C.G = g_; C.bid = b_; } while (0)
; __device__ __forceinline__ void attn_sample_wg(Ctx& C, int l, int bd, int h, const LAS float* biasl, LAS float* partO, LAS float* partML, const bool st) {
;     const int lane = C.lane, r = lane & 31, hi = lane >> 5, w = C.wave;
;     const int rp = (r & 19) | ((r & 4) << 1) | ((r & 8) >> 1);
;     const size_t grow0 = (size_t)MP + (size_t)bd * TS;
;     const bf16* U = C.U(); const bf16* KVt = C.KVt();
;     const float* cache_k = C.in[2] + ((size_t)(l * NBD + bd) * 512) * 512; const float* cache_v = C.in[3] + ((size_t)(l * NBD + bd) * 512) * 512;
; __global__ void __launch_bounds__(512) fwd_megakernel(Args args) {
;     ...
;             for (int rep = 0; rep < REP_P3; ++rep) { const bool st = (rep == REP_P3 - 1) || (C.ws == nullptr);
;             for (int u = C.bid; u < NBD * 8; u += C.G) { PHASE_BEGIN(); attn_sample_wg(C, l, u >> 3, u & 7, biasl, (LAS float*)(lds + 32768), (LAS float*)(lds + 98304), st); }
.LBB0_446:
	s_or_b64 exec, exec, s[4:5]
	v_readlane_b32 s4, v255, 40
	s_lshl_b32 s20, s4, 5
	s_mov_b32 s10, s2
	s_cmp_lg_u32 s26, 0x100
	s_cbranch_scc1 .Lsa_noperm
	s_and_b32 s10, s2, 7
	s_lshl_b32 s10, s10, 5
	s_lshr_b32 s11, s2, 3
	s_or_b32 s10, s10, s11
.Lsa_noperm:
	s_cmpk_gt_i32 s2, 0xff
	s_waitcnt lgkmcnt(0)
	s_barrier
	v_readlane_b32 s5, v255, 41
	s_cbranch_scc0 .LBB0_452
